# conv/pool mixer outputs (YS) written through with 16-byte sc1 stores
# speedup vs baseline: 1.0048x; 1.0048x over previous
.Lcv_nn0:
	v_lshlrev_b32_e32 v10, 16, v72
	v_and_b32_e32 v11, 0xffff0000, v72
	v_pk_mul_f32 v[2:3], v[2:3], v[10:11]
	v_lshlrev_b32_e32 v10, 16, v73
	v_and_b32_e32 v11, 0xffff0000, v73
	v_pk_mul_f32 v[4:5], v[4:5], v[10:11]
	v_lshlrev_b32_e32 v10, 16, v74
	v_and_b32_e32 v11, 0xffff0000, v74
	v_pk_mul_f32 v[6:7], v[6:7], v[10:11]
	v_lshlrev_b32_e32 v10, 16, v75
	v_and_b32_e32 v11, 0xffff0000, v75
	v_pk_mul_f32 v[8:9], v[8:9], v[10:11]
	s_nop 0
	v_cvt_pk_bf16_f32 v72, v2, v3
	v_cvt_pk_bf16_f32 v73, v4, v5
	v_cvt_pk_bf16_f32 v74, v6, v7
	v_cvt_pk_bf16_f32 v75, v8, v9
	s_mul_i32 s7, s12, 0xc00
	v_add_u32_e32 v247, s7, v244
	global_store_dwordx4 v247, v[72:75], s[36:37] sc1
	s_waitcnt vmcnt(15)
	v_lshlrev_b32_e32 v10, 16, v104
	v_and_b32_e32 v11, 0xffff0000, v104
	v_lshlrev_b32_e32 v12, 16, v108
	v_and_b32_e32 v13, 0xffff0000, v108
	v_pk_mul_f32 v[14:15], v[10:11], v[12:13]
	s_nop 0
	v_pk_mul_f32 v[2:3], v[182:183], v[14:15]
	v_lshlrev_b32_e32 v10, 16, v105
	v_and_b32_e32 v11, 0xffff0000, v105
	v_lshlrev_b32_e32 v12, 16, v109
	v_and_b32_e32 v13, 0xffff0000, v109
	v_pk_mul_f32 v[14:15], v[10:11], v[12:13]
	s_nop 0
	v_pk_mul_f32 v[4:5], v[184:185], v[14:15]
	v_lshlrev_b32_e32 v10, 16, v106
	v_and_b32_e32 v11, 0xffff0000, v106
	v_lshlrev_b32_e32 v12, 16, v110
	v_and_b32_e32 v13, 0xffff0000, v110
	v_pk_mul_f32 v[14:15], v[10:11], v[12:13]
	s_nop 0
	v_pk_mul_f32 v[6:7], v[186:187], v[14:15]
	v_lshlrev_b32_e32 v10, 16, v107
	v_and_b32_e32 v11, 0xffff0000, v107
	v_lshlrev_b32_e32 v12, 16, v111
	v_and_b32_e32 v13, 0xffff0000, v111
	v_pk_mul_f32 v[14:15], v[10:11], v[12:13]
	s_nop 0
	v_pk_mul_f32 v[8:9], v[188:189], v[14:15]
	s_bitcmp1_b32 s38, 2
	s_cbranch_scc1 .Lcv_np1
	v_lshlrev_b32_e32 v10, 16, v112
	v_and_b32_e32 v11, 0xffff0000, v112
	v_lshlrev_b32_e32 v12, 16, v116
	v_and_b32_e32 v13, 0xffff0000, v116
	v_pk_mul_f32 v[14:15], v[10:11], v[12:13]
	s_nop 0
	v_pk_fma_f32 v[2:3], v[174:175], v[14:15], v[2:3]
	v_lshlrev_b32_e32 v10, 16, v113
	v_and_b32_e32 v11, 0xffff0000, v113
	v_lshlrev_b32_e32 v12, 16, v117
	v_and_b32_e32 v13, 0xffff0000, v117
	v_pk_mul_f32 v[14:15], v[10:11], v[12:13]
	s_nop 0
	v_pk_fma_f32 v[4:5], v[176:177], v[14:15], v[4:5]
	v_lshlrev_b32_e32 v10, 16, v114
	v_and_b32_e32 v11, 0xffff0000, v114
	v_lshlrev_b32_e32 v12, 16, v118
	v_and_b32_e32 v13, 0xffff0000, v118
	v_pk_mul_f32 v[14:15], v[10:11], v[12:13]
	s_nop 0
	v_pk_fma_f32 v[6:7], v[178:179], v[14:15], v[6:7]
	v_lshlrev_b32_e32 v10, 16, v115
	v_and_b32_e32 v11, 0xffff0000, v115
	v_lshlrev_b32_e32 v12, 16, v119
	v_and_b32_e32 v13, 0xffff0000, v119
	v_pk_mul_f32 v[14:15], v[10:11], v[12:13]
	s_nop 0
	v_pk_fma_f32 v[8:9], v[180:181], v[14:15], v[8:9]

.Lcv_nn1:
	v_lshlrev_b32_e32 v10, 16, v100
	v_and_b32_e32 v11, 0xffff0000, v100
	v_pk_mul_f32 v[2:3], v[2:3], v[10:11]
	v_lshlrev_b32_e32 v10, 16, v101
	v_and_b32_e32 v11, 0xffff0000, v101
	v_pk_mul_f32 v[4:5], v[4:5], v[10:11]
	v_lshlrev_b32_e32 v10, 16, v102
	v_and_b32_e32 v11, 0xffff0000, v102
	v_pk_mul_f32 v[6:7], v[6:7], v[10:11]
	v_lshlrev_b32_e32 v10, 16, v103
	v_and_b32_e32 v11, 0xffff0000, v103
	v_pk_mul_f32 v[8:9], v[8:9], v[10:11]
	s_nop 0
	v_cvt_pk_bf16_f32 v100, v2, v3
	v_cvt_pk_bf16_f32 v101, v4, v5
	v_cvt_pk_bf16_f32 v102, v6, v7
	v_cvt_pk_bf16_f32 v103, v8, v9
	s_mul_i32 s7, s13, 0xc00
	v_add_u32_e32 v247, s7, v244
	global_store_dwordx4 v247, v[100:103], s[36:37] sc1
	s_waitcnt vmcnt(9)
	v_lshlrev_b32_e32 v10, 16, v132
	v_and_b32_e32 v11, 0xffff0000, v132
	v_lshlrev_b32_e32 v12, 16, v136
	v_and_b32_e32 v13, 0xffff0000, v136
	v_pk_mul_f32 v[14:15], v[10:11], v[12:13]
	s_nop 0
	v_pk_mul_f32 v[2:3], v[182:183], v[14:15]
	v_lshlrev_b32_e32 v10, 16, v133
	v_and_b32_e32 v11, 0xffff0000, v133
	v_lshlrev_b32_e32 v12, 16, v137
	v_and_b32_e32 v13, 0xffff0000, v137
	v_pk_mul_f32 v[14:15], v[10:11], v[12:13]
	s_nop 0
	v_pk_mul_f32 v[4:5], v[184:185], v[14:15]
	v_lshlrev_b32_e32 v10, 16, v134
	v_and_b32_e32 v11, 0xffff0000, v134
	v_lshlrev_b32_e32 v12, 16, v138
	v_and_b32_e32 v13, 0xffff0000, v138
	v_pk_mul_f32 v[14:15], v[10:11], v[12:13]
	s_nop 0
	v_pk_mul_f32 v[6:7], v[186:187], v[14:15]
	v_lshlrev_b32_e32 v10, 16, v135
	v_and_b32_e32 v11, 0xffff0000, v135
	v_lshlrev_b32_e32 v12, 16, v139
	v_and_b32_e32 v13, 0xffff0000, v139
	v_pk_mul_f32 v[14:15], v[10:11], v[12:13]
	s_nop 0
	v_pk_mul_f32 v[8:9], v[188:189], v[14:15]
	s_bitcmp1_b32 s38, 4
	s_cbranch_scc1 .Lcv_np2
	v_lshlrev_b32_e32 v10, 16, v140
	v_and_b32_e32 v11, 0xffff0000, v140
	v_lshlrev_b32_e32 v12, 16, v144
	v_and_b32_e32 v13, 0xffff0000, v144
	v_pk_mul_f32 v[14:15], v[10:11], v[12:13]
	s_nop 0
	v_pk_fma_f32 v[2:3], v[174:175], v[14:15], v[2:3]
	v_lshlrev_b32_e32 v10, 16, v141
	v_and_b32_e32 v11, 0xffff0000, v141
	v_lshlrev_b32_e32 v12, 16, v145
	v_and_b32_e32 v13, 0xffff0000, v145
	v_pk_mul_f32 v[14:15], v[10:11], v[12:13]
	s_nop 0
	v_pk_fma_f32 v[4:5], v[176:177], v[14:15], v[4:5]
	v_lshlrev_b32_e32 v10, 16, v142
	v_and_b32_e32 v11, 0xffff0000, v142
	v_lshlrev_b32_e32 v12, 16, v146
	v_and_b32_e32 v13, 0xffff0000, v146
	v_pk_mul_f32 v[14:15], v[10:11], v[12:13]
	s_nop 0
	v_pk_fma_f32 v[6:7], v[178:179], v[14:15], v[6:7]
	v_lshlrev_b32_e32 v10, 16, v143
	v_and_b32_e32 v11, 0xffff0000, v143
	v_lshlrev_b32_e32 v12, 16, v147
	v_and_b32_e32 v13, 0xffff0000, v147
	v_pk_mul_f32 v[14:15], v[10:11], v[12:13]
	s_nop 0
	v_pk_fma_f32 v[8:9], v[180:181], v[14:15], v[8:9]

.Lcv_nn2:
	v_lshlrev_b32_e32 v10, 16, v128
	v_and_b32_e32 v11, 0xffff0000, v128
	v_pk_mul_f32 v[2:3], v[2:3], v[10:11]
	v_lshlrev_b32_e32 v10, 16, v129
	v_and_b32_e32 v11, 0xffff0000, v129
	v_pk_mul_f32 v[4:5], v[4:5], v[10:11]
	v_lshlrev_b32_e32 v10, 16, v130
	v_and_b32_e32 v11, 0xffff0000, v130
	v_pk_mul_f32 v[6:7], v[6:7], v[10:11]
	v_lshlrev_b32_e32 v10, 16, v131
	v_and_b32_e32 v11, 0xffff0000, v131
	v_pk_mul_f32 v[8:9], v[8:9], v[10:11]
	s_nop 0
	v_cvt_pk_bf16_f32 v128, v2, v3
	v_cvt_pk_bf16_f32 v129, v4, v5
	v_cvt_pk_bf16_f32 v130, v6, v7
	v_cvt_pk_bf16_f32 v131, v8, v9
	s_mul_i32 s7, s14, 0xc00
	v_add_u32_e32 v247, s7, v244
	global_store_dwordx4 v247, v[128:131], s[36:37] sc1
	s_waitcnt vmcnt(3)
	v_lshlrev_b32_e32 v10, 16, v216
	v_and_b32_e32 v11, 0xffff0000, v216
	v_lshlrev_b32_e32 v12, 16, v220
	v_and_b32_e32 v13, 0xffff0000, v220
	v_pk_mul_f32 v[14:15], v[10:11], v[12:13]
	s_nop 0
	v_pk_mul_f32 v[2:3], v[182:183], v[14:15]
	v_lshlrev_b32_e32 v10, 16, v217
	v_and_b32_e32 v11, 0xffff0000, v217
	v_lshlrev_b32_e32 v12, 16, v221
	v_and_b32_e32 v13, 0xffff0000, v221
	v_pk_mul_f32 v[14:15], v[10:11], v[12:13]
	s_nop 0
	v_pk_mul_f32 v[4:5], v[184:185], v[14:15]
	v_lshlrev_b32_e32 v10, 16, v218
	v_and_b32_e32 v11, 0xffff0000, v218
	v_lshlrev_b32_e32 v12, 16, v222
	v_and_b32_e32 v13, 0xffff0000, v222
	v_pk_mul_f32 v[14:15], v[10:11], v[12:13]
	s_nop 0
	v_pk_mul_f32 v[6:7], v[186:187], v[14:15]
	v_lshlrev_b32_e32 v10, 16, v219
	v_and_b32_e32 v11, 0xffff0000, v219
	v_lshlrev_b32_e32 v12, 16, v223
	v_and_b32_e32 v13, 0xffff0000, v223
	v_pk_mul_f32 v[14:15], v[10:11], v[12:13]
	s_nop 0
	v_pk_mul_f32 v[8:9], v[188:189], v[14:15]
	s_bitcmp1_b32 s38, 6
	s_cbranch_scc1 .Lcv_np3
	v_lshlrev_b32_e32 v10, 16, v224
	v_and_b32_e32 v11, 0xffff0000, v224
	v_lshlrev_b32_e32 v12, 16, v228
	v_and_b32_e32 v13, 0xffff0000, v228
	v_pk_mul_f32 v[14:15], v[10:11], v[12:13]
	s_nop 0
	v_pk_fma_f32 v[2:3], v[174:175], v[14:15], v[2:3]
	v_lshlrev_b32_e32 v10, 16, v225
	v_and_b32_e32 v11, 0xffff0000, v225
	v_lshlrev_b32_e32 v12, 16, v229
	v_and_b32_e32 v13, 0xffff0000, v229
	v_pk_mul_f32 v[14:15], v[10:11], v[12:13]
	s_nop 0
	v_pk_fma_f32 v[4:5], v[176:177], v[14:15], v[4:5]
	v_lshlrev_b32_e32 v10, 16, v226
	v_and_b32_e32 v11, 0xffff0000, v226
	v_lshlrev_b32_e32 v12, 16, v230
	v_and_b32_e32 v13, 0xffff0000, v230
	v_pk_mul_f32 v[14:15], v[10:11], v[12:13]
	s_nop 0
	v_pk_fma_f32 v[6:7], v[178:179], v[14:15], v[6:7]
	v_lshlrev_b32_e32 v10, 16, v227
	v_and_b32_e32 v11, 0xffff0000, v227
	v_lshlrev_b32_e32 v12, 16, v231
	v_and_b32_e32 v13, 0xffff0000, v231
	v_pk_mul_f32 v[14:15], v[10:11], v[12:13]
	s_nop 0
	v_pk_fma_f32 v[8:9], v[180:181], v[14:15], v[8:9]

.Lcv_nn3:
	v_lshlrev_b32_e32 v10, 16, v212
	v_and_b32_e32 v11, 0xffff0000, v212
	v_pk_mul_f32 v[2:3], v[2:3], v[10:11]
	v_lshlrev_b32_e32 v10, 16, v213
	v_and_b32_e32 v11, 0xffff0000, v213
	v_pk_mul_f32 v[4:5], v[4:5], v[10:11]
	v_lshlrev_b32_e32 v10, 16, v214
	v_and_b32_e32 v11, 0xffff0000, v214
	v_pk_mul_f32 v[6:7], v[6:7], v[10:11]
	v_lshlrev_b32_e32 v10, 16, v215
	v_and_b32_e32 v11, 0xffff0000, v215
	v_pk_mul_f32 v[8:9], v[8:9], v[10:11]
	s_nop 0
	v_cvt_pk_bf16_f32 v212, v2, v3
	v_cvt_pk_bf16_f32 v213, v4, v5
	v_cvt_pk_bf16_f32 v214, v6, v7
	v_cvt_pk_bf16_f32 v215, v8, v9
	s_mul_i32 s7, s15, 0xc00
	v_add_u32_e32 v247, s7, v244
	global_store_dwordx4 v247, v[212:215], s[36:37] sc1

.Lp2_rw35:
	s_mov_b64 exec, -1
	s_add_i32 s15, s14, 0
	v_sub_u32_e32 v247, s15, v245
	v_max_i32_e32 v247, 0, v247
	v_add_u32_e32 v248, s15, v245
	v_min_i32_e32 v248, s13, v248
	v_sub_u32_e32 v249, v248, v247
	v_cvt_f32_i32_e32 v154, v249
	v_div_scale_f32 v155, s[2:3], v154, v154, 1.0
	v_rcp_f32_e32 v156, v155
	s_nop 0
	v_fma_f32 v157, -v155, v156, 1.0
	v_fmac_f32_e32 v156, v157, v156
	v_div_scale_f32 v157, vcc, 1.0, v154, 1.0
	v_mul_f32_e32 v158, v157, v156
	v_fma_f32 v159, -v155, v158, v157
	v_fmac_f32_e32 v158, v159, v156
	v_fma_f32 v157, -v155, v158, v157
	s_nop 1
	v_div_fmas_f32 v157, v157, v156, v158
	v_div_fixup_f32 v157, v157, v154, 1.0
	v_mov_b32_e32 v156, v157
	v_pk_fma_f32 v[212:213], v[156:157], v[212:213], v[66:67] op_sel_hi:[0,1,1] neg_lo:[0,0,1] neg_hi:[0,0,1]
	v_pk_fma_f32 v[214:215], v[156:157], v[214:215], v[68:69] op_sel_hi:[0,1,1] neg_lo:[0,0,1] neg_hi:[0,0,1]
	v_pk_fma_f32 v[216:217], v[156:157], v[216:217], v[70:71] op_sel_hi:[0,1,1] neg_lo:[0,0,1] neg_hi:[0,0,1]
	v_pk_fma_f32 v[218:219], v[156:157], v[218:219], v[72:73] op_sel_hi:[0,1,1] neg_lo:[0,0,1] neg_hi:[0,0,1]
	s_nop 0
	v_cvt_pk_bf16_f32 v220, v212, v213
	v_cvt_pk_bf16_f32 v221, v214, v215
	v_cvt_pk_bf16_f32 v222, v216, v217
	v_cvt_pk_bf16_f32 v223, v218, v219
	s_add_u32 s2, s12, 0
	s_mul_i32 s2, s2, 0xc00
	v_add_u32_e32 v246, s2, v244
	global_store_dwordx4 v246, v[220:223], s[36:37] offset:2048 sc1
	v_mov_b32_e32 v212, 0
	v_mov_b32_e32 v213, 0
	v_mov_b32_e32 v214, 0
	v_mov_b32_e32 v215, 0
	v_mov_b32_e32 v216, 0
	v_mov_b32_e32 v217, 0
	v_mov_b32_e32 v218, 0
	v_mov_b32_e32 v219, 0
	s_add_i32 s15, s14, -7
	s_cmp_lt_u32 s15, s13
	s_cbranch_scc0 .Lp2_rw36
	s_mov_b64 exec, s[38:39]
	v_add_f32_e32 v212, v212, v10
	v_add_f32_e32 v213, v213, v11
	v_add_f32_e32 v214, v214, v12
	v_add_f32_e32 v215, v215, v13
	v_add_f32_e32 v216, v216, v14
	v_add_f32_e32 v217, v217, v15
	v_add_f32_e32 v218, v218, v16
	v_add_f32_e32 v219, v219, v17

.Lp2_rw51:
	s_mov_b64 exec, -1
	s_add_i32 s15, s14, 1
	v_sub_u32_e32 v247, s15, v245
	v_max_i32_e32 v247, 0, v247
	v_add_u32_e32 v248, s15, v245
	v_min_i32_e32 v248, s13, v248
	v_sub_u32_e32 v249, v248, v247
	v_cvt_f32_i32_e32 v154, v249
	v_div_scale_f32 v155, s[2:3], v154, v154, 1.0
	v_rcp_f32_e32 v156, v155
	s_nop 0
	v_fma_f32 v157, -v155, v156, 1.0
	v_fmac_f32_e32 v156, v157, v156
	v_div_scale_f32 v157, vcc, 1.0, v154, 1.0
	v_mul_f32_e32 v158, v157, v156
	v_fma_f32 v159, -v155, v158, v157
	v_fmac_f32_e32 v158, v159, v156
	v_fma_f32 v157, -v155, v158, v157
	s_nop 1
	v_div_fmas_f32 v157, v157, v156, v158
	v_div_fixup_f32 v157, v157, v154, 1.0
	v_mov_b32_e32 v156, v157
	v_pk_fma_f32 v[212:213], v[156:157], v[212:213], v[74:75] op_sel_hi:[0,1,1] neg_lo:[0,0,1] neg_hi:[0,0,1]
	v_pk_fma_f32 v[214:215], v[156:157], v[214:215], v[76:77] op_sel_hi:[0,1,1] neg_lo:[0,0,1] neg_hi:[0,0,1]
	v_pk_fma_f32 v[216:217], v[156:157], v[216:217], v[78:79] op_sel_hi:[0,1,1] neg_lo:[0,0,1] neg_hi:[0,0,1]
	v_pk_fma_f32 v[218:219], v[156:157], v[218:219], v[80:81] op_sel_hi:[0,1,1] neg_lo:[0,0,1] neg_hi:[0,0,1]
	s_nop 0
	v_cvt_pk_bf16_f32 v220, v212, v213
	v_cvt_pk_bf16_f32 v221, v214, v215
	v_cvt_pk_bf16_f32 v222, v216, v217
	v_cvt_pk_bf16_f32 v223, v218, v219
	s_add_u32 s2, s12, 1
	s_mul_i32 s2, s2, 0xc00
	v_add_u32_e32 v246, s2, v244
	global_store_dwordx4 v246, v[220:223], s[36:37] offset:2048 sc1
	v_mov_b32_e32 v212, 0
	v_mov_b32_e32 v213, 0
	v_mov_b32_e32 v214, 0
	v_mov_b32_e32 v215, 0
	v_mov_b32_e32 v216, 0
	v_mov_b32_e32 v217, 0
	v_mov_b32_e32 v218, 0
	v_mov_b32_e32 v219, 0
	s_add_i32 s15, s14, -6
	s_cmp_lt_u32 s15, s13
	s_cbranch_scc0 .Lp2_rw52
	s_mov_b64 exec, s[38:39]
	v_add_f32_e32 v212, v212, v18
	v_add_f32_e32 v213, v213, v19
	v_add_f32_e32 v214, v214, v20
	v_add_f32_e32 v215, v215, v21
	v_add_f32_e32 v216, v216, v22
	v_add_f32_e32 v217, v217, v23
	v_add_f32_e32 v218, v218, v24
	v_add_f32_e32 v219, v219, v25

.Lp2_rw67:
	s_mov_b64 exec, -1
	s_add_i32 s15, s14, 2
	v_sub_u32_e32 v247, s15, v245
	v_max_i32_e32 v247, 0, v247
	v_add_u32_e32 v248, s15, v245
	v_min_i32_e32 v248, s13, v248
	v_sub_u32_e32 v249, v248, v247
	v_cvt_f32_i32_e32 v154, v249
	v_div_scale_f32 v155, s[2:3], v154, v154, 1.0
	v_rcp_f32_e32 v156, v155
	s_nop 0
	v_fma_f32 v157, -v155, v156, 1.0
	v_fmac_f32_e32 v156, v157, v156
	v_div_scale_f32 v157, vcc, 1.0, v154, 1.0
	v_mul_f32_e32 v158, v157, v156
	v_fma_f32 v159, -v155, v158, v157
	v_fmac_f32_e32 v158, v159, v156
	v_fma_f32 v157, -v155, v158, v157
	s_nop 1
	v_div_fmas_f32 v157, v157, v156, v158
	v_div_fixup_f32 v157, v157, v154, 1.0
	v_mov_b32_e32 v156, v157
	v_pk_fma_f32 v[212:213], v[156:157], v[212:213], v[82:83] op_sel_hi:[0,1,1] neg_lo:[0,0,1] neg_hi:[0,0,1]
	v_pk_fma_f32 v[214:215], v[156:157], v[214:215], v[84:85] op_sel_hi:[0,1,1] neg_lo:[0,0,1] neg_hi:[0,0,1]
	v_pk_fma_f32 v[216:217], v[156:157], v[216:217], v[86:87] op_sel_hi:[0,1,1] neg_lo:[0,0,1] neg_hi:[0,0,1]
	v_pk_fma_f32 v[218:219], v[156:157], v[218:219], v[88:89] op_sel_hi:[0,1,1] neg_lo:[0,0,1] neg_hi:[0,0,1]
	s_nop 0
	v_cvt_pk_bf16_f32 v220, v212, v213
	v_cvt_pk_bf16_f32 v221, v214, v215
	v_cvt_pk_bf16_f32 v222, v216, v217
	v_cvt_pk_bf16_f32 v223, v218, v219
	s_add_u32 s2, s12, 2
	s_mul_i32 s2, s2, 0xc00
	v_add_u32_e32 v246, s2, v244
	global_store_dwordx4 v246, v[220:223], s[36:37] offset:2048 sc1
	v_mov_b32_e32 v212, 0
	v_mov_b32_e32 v213, 0
	v_mov_b32_e32 v214, 0
	v_mov_b32_e32 v215, 0
	v_mov_b32_e32 v216, 0
	v_mov_b32_e32 v217, 0
	v_mov_b32_e32 v218, 0
	v_mov_b32_e32 v219, 0
	s_add_i32 s15, s14, -5
	s_cmp_lt_u32 s15, s13
	s_cbranch_scc0 .Lp2_rw68
	s_mov_b64 exec, s[38:39]
	v_add_f32_e32 v212, v212, v26
	v_add_f32_e32 v213, v213, v27
	v_add_f32_e32 v214, v214, v28
	v_add_f32_e32 v215, v215, v29
	v_add_f32_e32 v216, v216, v30
	v_add_f32_e32 v217, v217, v31
	v_add_f32_e32 v218, v218, v32
	v_add_f32_e32 v219, v219, v33

.Lp2_rw83:
	s_mov_b64 exec, -1
	s_add_i32 s15, s14, 3
	v_sub_u32_e32 v247, s15, v245
	v_max_i32_e32 v247, 0, v247
	v_add_u32_e32 v248, s15, v245
	v_min_i32_e32 v248, s13, v248
	v_sub_u32_e32 v249, v248, v247
	v_cvt_f32_i32_e32 v154, v249
	v_div_scale_f32 v155, s[2:3], v154, v154, 1.0
	v_rcp_f32_e32 v156, v155
	s_nop 0
	v_fma_f32 v157, -v155, v156, 1.0
	v_fmac_f32_e32 v156, v157, v156
	v_div_scale_f32 v157, vcc, 1.0, v154, 1.0
	v_mul_f32_e32 v158, v157, v156
	v_fma_f32 v159, -v155, v158, v157
	v_fmac_f32_e32 v158, v159, v156
	v_fma_f32 v157, -v155, v158, v157
	s_nop 1
	v_div_fmas_f32 v157, v157, v156, v158
	v_div_fixup_f32 v157, v157, v154, 1.0
	v_mov_b32_e32 v156, v157
	v_pk_fma_f32 v[212:213], v[156:157], v[212:213], v[90:91] op_sel_hi:[0,1,1] neg_lo:[0,0,1] neg_hi:[0,0,1]
	v_pk_fma_f32 v[214:215], v[156:157], v[214:215], v[92:93] op_sel_hi:[0,1,1] neg_lo:[0,0,1] neg_hi:[0,0,1]
	v_pk_fma_f32 v[216:217], v[156:157], v[216:217], v[94:95] op_sel_hi:[0,1,1] neg_lo:[0,0,1] neg_hi:[0,0,1]
	v_pk_fma_f32 v[218:219], v[156:157], v[218:219], v[96:97] op_sel_hi:[0,1,1] neg_lo:[0,0,1] neg_hi:[0,0,1]
	s_nop 0
	v_cvt_pk_bf16_f32 v220, v212, v213
	v_cvt_pk_bf16_f32 v221, v214, v215
	v_cvt_pk_bf16_f32 v222, v216, v217
	v_cvt_pk_bf16_f32 v223, v218, v219
	s_add_u32 s2, s12, 3
	s_mul_i32 s2, s2, 0xc00
	v_add_u32_e32 v246, s2, v244
	global_store_dwordx4 v246, v[220:223], s[36:37] offset:2048 sc1
	s_branch .LBB0_403
